# LN1P2: LN1 row loop keeps two rows of loads in flight per wave (alternating landing zones, scale/shift vectors requested first, one counted wait); on top of DPP+CONV5
# baseline (speedup 1.0000x reference)
; __device__ __forceinline__ void phase_ln1(const Params& p, int g, int gw, int NGW, int lane) {
;     ...
;     f32x4 gaH[4], beH[4];
; #pragma unroll
;     for (int j = 0; j < 4; ++j) { gaH[j] = *(const f32x4*)(p.ln1_g + 4 * lane + 256 * j); beH[j] = *(const f32x4*)(p.ln1_b + 4 * lane + 256 * j); }
;     f32x4 nx[4]; u32x2 nb[4];
;     if (gw < TG) {
; #pragma unroll
;         for (int j = 0; j < 4; ++j) { nx[j] = *(const f32x4*)(xbase + (size_t)gw * DM + 4 * lane + 256 * j); nb[j] = *(const u32x2*)(brbase + (size_t)gw * DM + 4 * lane + 256 * j); } }
;     ...
;         if (row + NGW < TG) { const size_t nr = (size_t)(row + NGW) * DM;
; #pragma unroll
;             for (int j = 0; j < 4; ++j) { nx[j] = *(const f32x4*)(xbase + nr + 4 * lane + 256 * j); nb[j] = *(const u32x2*)(brbase + nr + 4 * lane + 256 * j); } }
.LBB0_301:
	s_andn2_b64 vcc, exec, s[0:1]
	s_cbranch_vccnz .LBB0_330
	s_cmp_gt_i32 s79, 6
	s_mov_b64 s[0:1], -1
	s_cbranch_scc0 .LBB0_309
	s_cmpk_gt_i32 s26, 0x7fff
	s_cbranch_scc1 .LBB0_308
	v_lshlrev_b32_e32 v192, 4, v244
	s_waitcnt lgkmcnt(0)
	global_load_dwordx4 v[0:3], v192, s[16:17]
	global_load_dwordx4 v[4:7], v192, s[18:19]
	global_load_dwordx4 v[8:11], v192, s[16:17] offset:1024
	global_load_dwordx4 v[12:15], v192, s[18:19] offset:1024
	global_load_dwordx4 v[16:19], v192, s[16:17] offset:2048
	global_load_dwordx4 v[20:23], v192, s[18:19] offset:2048
	global_load_dwordx4 v[24:27], v192, s[16:17] offset:3072
	global_load_dwordx4 v[28:31], v192, s[18:19] offset:3072
	s_add_u32 s0, s94, 0x17900000
	s_addc_u32 s1, s95, 0
	s_add_u32 s2, s44, s20
	s_addc_u32 s3, s45, s21
	s_ashr_i32 s27, s26, 31
	s_lshl_b64 s[6:7], s[26:27], 12
	s_add_u32 s4, s2, s6
	s_addc_u32 s5, s3, s7
	s_lshl_b64 s[8:9], s[26:27], 11
	s_add_u32 s10, s0, s8
	s_addc_u32 s11, s1, s9
	v_lshlrev_b32_e32 v32, 3, v244
	global_load_dwordx2 v[86:87], v32, s[10:11]
	global_load_dwordx2 v[84:85], v32, s[10:11] offset:512
	global_load_dwordx2 v[82:83], v32, s[10:11] offset:1024
	global_load_dwordx2 v[80:81], v32, s[10:11] offset:1536
	global_load_dwordx4 v[60:63], v192, s[4:5]
	global_load_dwordx4 v[56:59], v192, s[4:5] offset:1024
	global_load_dwordx4 v[52:55], v192, s[4:5] offset:2048
	global_load_dwordx4 v[48:51], v192, s[4:5] offset:3072
	v_lshlrev_b32_e32 v34, 2, v244
	v_mov_b32_e32 v33, v193
	v_or_b32_e32 v36, 0x100, v34
	v_or_b32_e32 v38, 0x200, v34
	v_or_b32_e32 v40, 0x300, v34
	s_mov_b32 s4, s26
	v_xor_b32_e32 v88, 4, v34
	v_xor_b32_e32 v89, 8, v34
	v_xor_b32_e32 v90, 16, v34
	v_xor_b32_e32 v91, 32, v34
	v_xor_b32_e32 v92, 64, v34
	v_xor_b32_e32 v93, 0x80, v34
	v_lshlrev_b32_e32 v94, 2, v34
	v_lshl_add_u64 v[64:65], s[0:1], 0, v[32:33]
	v_lshlrev_b32_e32 v95, 2, v36
	v_lshlrev_b32_e32 v96, 2, v38
	v_lshlrev_b32_e32 v97, 2, v40
	v_lshl_add_u64 v[66:67], s[2:3], 0, v[192:193]
	v_lshl_or_b32 v68, v244, 4, s6
	v_mov_b32_e32 v69, s7
	v_lshl_or_b32 v70, v244, 3, s8
	v_mov_b32_e32 v71, s9
	s_waitcnt vmcnt(0)
	v_mov_b64_e32 v[78:79], v[86:87]
	s_waitcnt vmcnt(6)
	v_mov_b64_e32 v[76:77], v[84:85]
	s_waitcnt vmcnt(5)
	v_mov_b64_e32 v[74:75], v[82:83]
	s_waitcnt vmcnt(4)
	v_mov_b64_e32 v[72:73], v[80:81]
	s_waitcnt vmcnt(0)
	v_readlane_b32 s0, v255, 12
	s_mov_b32 s10, 0
	s_nop 0
	s_add_i32 s8, s26, s0
	s_cmpk_gt_i32 s8, 0x7fff
	s_cbranch_scc1 .Lln1_pro_done
	s_ashr_i32 s9, s8, 31
	s_lshl_b64 s[6:7], s[8:9], 12
	v_lshl_add_u64 v[44:45], v[66:67], 0, s[6:7]
	s_lshl_b64 s[6:7], s[8:9], 11
	v_lshl_add_u64 v[72:73], v[64:65], 0, s[6:7]
	global_load_dwordx4 v[32:35], v[44:45], off
	global_load_dwordx4 v[36:39], v[44:45], off offset:1024
	global_load_dwordx4 v[40:43], v[44:45], off offset:2048
	s_nop 0
	global_load_dwordx4 v[44:47], v[44:45], off offset:3072
	s_nop 0
	global_load_dwordx2 v[78:79], v[72:73], off
	global_load_dwordx2 v[76:77], v[72:73], off offset:512
	global_load_dwordx2 v[74:75], v[72:73], off offset:1024
	s_nop 0
	global_load_dwordx2 v[72:73], v[72:73], off offset:1536

; __device__ __forceinline__ float bflo(unsigned w) { return __uint_as_float(w << 16); }
; __device__ __forceinline__ float bfhi(unsigned w) { return __uint_as_float(w & 0xffff0000u); }
; __device__ __forceinline__ void phase_ln1(const Params& p, int g, int gw, int NGW, int lane) {
;     ...
;         f32x4 v[4]; float s = 0.f;
; #pragma unroll
;         for (int j = 0; j < 4; ++j) { const u32x2 bw = nb[j];
;             v[j] = nx[j] * ALPHA + (f32x4){bflo(bw.x), bfhi(bw.x), bflo(bw.y), bfhi(bw.y)}; s += (v[j].x + v[j].y) + (v[j].z + v[j].w); }
;         if (row + NGW < TG) { const size_t nr = (size_t)(row + NGW) * DM;
; #pragma unroll
;             for (int j = 0; j < 4; ++j) { nx[j] = *(const f32x4*)(xbase + nr + 4 * lane + 256 * j); nb[j] = *(const u32x2*)(brbase + nr + 4 * lane + 256 * j); } }
;         float mean = wave_sum(s, lane) * (1.f / DM); float s2 = 0.f;
; #pragma unroll
;         for (int j = 0; j < 4; ++j) { v[j] = v[j] - mean; s2 += (v[j].x * v[j].x + v[j].y * v[j].y) + (v[j].z * v[j].z + v[j].w * v[j].w); }
;         float rstd = __builtin_amdgcn_rsqf(wave_sum(s2, lane) * (1.f / DM) + 1e-6f);
;         s = 0.f;
; #pragma unroll
;         for (int j = 0; j < 4; ++j) { const int col = 4 * lane + 256 * j; const f32x4 ga = gaH[j], be = beH[j];
;             v[j] = v[j] * rstd * ga + be; *(f32x4*)(xr + col) = v[j]; s += (v[j].x + v[j].y) + (v[j].z + v[j].w); }
.LBB0_305:
	v_lshlrev_b32_e32 v98, 16, v86
	v_and_b32_e32 v99, 0xffff0000, v86
	v_lshlrev_b32_e32 v86, 16, v87
	v_and_b32_e32 v87, 0xffff0000, v87
	v_pk_fma_f32 v[62:63], v[62:63], s[70:71], v[86:87] op_sel_hi:[1,0,1]
	v_pk_fma_f32 v[60:61], v[60:61], s[70:71], v[98:99] op_sel_hi:[1,0,1]
	v_add_f32_e32 v87, v62, v63
	v_add_f32_e32 v86, v60, v61
	v_add_f32_e32 v86, v86, v87
	v_add_f32_e32 v98, 0, v86
	v_lshlrev_b32_e32 v86, 16, v84
	v_and_b32_e32 v87, 0xffff0000, v84
	v_lshlrev_b32_e32 v84, 16, v85
	v_and_b32_e32 v85, 0xffff0000, v85
	v_pk_fma_f32 v[58:59], v[58:59], s[70:71], v[84:85] op_sel_hi:[1,0,1]
	v_pk_fma_f32 v[56:57], v[56:57], s[70:71], v[86:87] op_sel_hi:[1,0,1]
	v_add_f32_e32 v85, v58, v59
	v_add_f32_e32 v84, v56, v57
	v_add_f32_e32 v84, v84, v85
	v_add_f32_e32 v86, v84, v98
	v_lshlrev_b32_e32 v84, 16, v82
	v_and_b32_e32 v85, 0xffff0000, v82
	v_lshlrev_b32_e32 v82, 16, v83
	v_and_b32_e32 v83, 0xffff0000, v83
	v_pk_fma_f32 v[82:83], v[54:55], s[70:71], v[82:83] op_sel_hi:[1,0,1]
	v_pk_fma_f32 v[84:85], v[52:53], s[70:71], v[84:85] op_sel_hi:[1,0,1]
	v_add_f32_e32 v53, v82, v83
	v_add_f32_e32 v52, v84, v85
	v_add_f32_e32 v52, v52, v53
	v_add_f32_e32 v98, v52, v86
	v_lshlrev_b32_e32 v52, 16, v80
	v_and_b32_e32 v53, 0xffff0000, v80
	v_lshlrev_b32_e32 v54, 16, v81
	v_and_b32_e32 v55, 0xffff0000, v81
	v_pk_fma_f32 v[80:81], v[50:51], s[70:71], v[54:55] op_sel_hi:[1,0,1]
	v_pk_fma_f32 v[86:87], v[48:49], s[70:71], v[52:53] op_sel_hi:[1,0,1]
	v_add_f32_e32 v49, v80, v81
	v_add_f32_e32 v48, v86, v87
	v_add_f32_e32 v48, v48, v49
	v_add_f32_e32 v48, v48, v98
	s_nop 1
	v_add_f32_dpp v48, v48, v48 quad_perm:[1,0,3,2] row_mask:0xf bank_mask:0xf
	s_nop 1
	v_add_f32_dpp v48, v48, v48 quad_perm:[2,3,0,1] row_mask:0xf bank_mask:0xf
	s_nop 1
	v_add_f32_dpp v48, v48, v48 row_half_mirror row_mask:0xf bank_mask:0xf
	s_mov_b32 s1, 0xf900000
	s_nop 1
	v_add_f32_dpp v48, v48, v48 row_mirror row_mask:0xf bank_mask:0xf
	v_mov_b32_e32 v49, v48
	s_nop 1
	v_permlane16_swap_b32_e32 v48, v49
	v_add_f32_e32 v48, v48, v49
	v_mov_b32_e32 v49, v48
	s_nop 1
	v_permlane32_swap_b32_e32 v48, v49
	v_add_f32_e32 v98, v48, v49
	v_fmamk_f32 v61, v98, 0xba800000, v61
	v_fmac_f32_e32 v60, 0xba800000, v98
	v_fmamk_f32 v63, v98, 0xba800000, v63
	v_fmac_f32_e32 v62, 0xba800000, v98
	v_pk_mul_f32 v[48:49], v[62:63], v[62:63]
	v_pk_mul_f32 v[50:51], v[60:61], v[60:61]
	v_fmamk_f32 v57, v98, 0xba800000, v57
	v_pk_mov_b32 v[52:53], v[50:51], v[48:49] op_sel:[1,0]
	v_mov_b32_e32 v51, v49
	v_pk_add_f32 v[48:49], v[52:53], v[50:51]
	v_fmac_f32_e32 v56, 0xba800000, v98
	v_fmamk_f32 v59, v98, 0xba800000, v59
	v_fmac_f32_e32 v58, 0xba800000, v98
	v_pk_add_f32 v[48:49], v[48:49], v[48:49] op_sel_hi:[0,1]
	v_pk_mul_f32 v[50:51], v[58:59], v[58:59]
	v_pk_mul_f32 v[52:53], v[56:57], v[56:57]
	v_fmac_f32_e32 v84, 0xba800000, v98
	v_pk_mov_b32 v[54:55], v[52:53], v[50:51] op_sel:[1,0]
	v_mov_b32_e32 v53, v51
	v_fmamk_f32 v85, v98, 0xba800000, v85
	v_fmac_f32_e32 v82, 0xba800000, v98
	v_mul_f32_e32 v48, v84, v84
	v_pk_add_f32 v[50:51], v[54:55], v[52:53]
	v_fmamk_f32 v83, v98, 0xba800000, v83
	v_pk_fma_f32 v[52:53], v[84:85], v[84:85], v[48:49] op_sel_hi:[1,1,0]
	v_mul_f32_e32 v48, v82, v82
	v_pk_add_f32 v[50:51], v[50:51], v[50:51] op_sel_hi:[0,1]
	v_pk_fma_f32 v[54:55], v[82:83], v[82:83], v[48:49] op_sel_hi:[1,1,0]
	v_fmamk_f32 v81, v98, 0xba800000, v81
	v_fmac_f32_e32 v80, 0xba800000, v98
	v_fmamk_f32 v87, v98, 0xba800000, v87
	v_fmac_f32_e32 v86, 0xba800000, v98
	v_mul_f32_e32 v52, v86, v86
	v_mul_f32_e32 v54, v87, v87
	v_mul_f32_e32 v48, v80, v80
	v_mul_f32_e32 v50, v81, v81
	v_pk_add_f32 v[52:53], v[52:53], v[54:55]
	v_pk_add_f32 v[48:49], v[48:49], v[50:51]
	s_nop 0
	v_pk_add_f32 v[48:49], v[52:53], v[48:49]
	v_lshl_add_u64 v[52:53], s[94:95], 0, v[68:69]
	v_add_f32_e32 v48, v48, v49
	v_add_co_u32_e32 v100, vcc, s89, v52
	s_nop 1
	v_add_f32_dpp v48, v48, v48 quad_perm:[1,0,3,2] row_mask:0xf bank_mask:0xf
	v_addc_co_u32_e32 v101, vcc, 0, v53, vcc
	s_nop 1
	v_add_f32_dpp v48, v48, v48 quad_perm:[2,3,0,1] row_mask:0xf bank_mask:0xf
	s_nop 1
	v_add_f32_dpp v48, v48, v48 row_half_mirror row_mask:0xf bank_mask:0xf
	s_nop 1
	v_add_f32_dpp v48, v48, v48 row_mirror row_mask:0xf bank_mask:0xf
	v_mov_b32_e32 v49, v48
	s_nop 1
	v_permlane16_swap_b32_e32 v48, v49
	v_add_f32_e32 v48, v48, v49
	v_mov_b32_e32 v49, v48
	s_nop 1
	v_permlane32_swap_b32_e32 v48, v49
	v_add_f32_e32 v48, v48, v49
	v_fmamk_f32 v48, v48, 0x3a800000, v238
	v_rsq_f32_e32 v98, v48
	s_nop 0
	v_pk_mul_f32 v[50:51], v[62:63], v[98:99] op_sel_hi:[1,0]
	v_pk_mul_f32 v[48:49], v[60:61], v[98:99] op_sel_hi:[1,0]
	v_pk_fma_f32 v[50:51], v[2:3], v[50:51], v[6:7]
	v_pk_fma_f32 v[48:49], v[0:1], v[48:49], v[4:5]
	v_mov_b32_e32 v55, v51
	v_pk_mov_b32 v[52:53], v[48:49], v[50:51] op_sel:[1,0]
	v_mov_b32_e32 v54, v48
	v_pk_add_f32 v[52:53], v[52:53], v[54:55]
	global_store_dwordx4 v[100:101], v[48:51], off
	v_add_f32_e32 v52, v52, v53
	v_add_f32_e32 v99, 0, v52
	v_pk_mul_f32 v[54:55], v[58:59], v[98:99] op_sel_hi:[1,0]
	v_pk_mul_f32 v[52:53], v[56:57], v[98:99] op_sel_hi:[1,0]
	v_pk_fma_f32 v[54:55], v[10:11], v[54:55], v[14:15]
	v_pk_fma_f32 v[52:53], v[8:9], v[52:53], v[12:13]
	v_mov_b32_e32 v59, v55
	v_pk_mov_b32 v[56:57], v[52:53], v[54:55] op_sel:[1,0]
	v_mov_b32_e32 v58, v52
	v_pk_add_f32 v[56:57], v[56:57], v[58:59]
	v_pk_mul_f32 v[58:59], v[82:83], v[98:99] op_sel_hi:[1,0]
	v_pk_add_f32 v[102:103], v[56:57], v[56:57] op_sel_hi:[0,1]
	v_pk_mul_f32 v[56:57], v[84:85], v[98:99] op_sel_hi:[1,0]
	v_pk_mul_f32 v[60:61], v[86:87], v[98:99] op_sel_hi:[1,0]
	v_pk_mul_f32 v[62:63], v[80:81], v[98:99] op_sel_hi:[1,0]
; __device__ __forceinline__ void phase_ln1(const Params& p, int g, int gw, int NGW, int lane) {
;     ...
;             v[j] = v[j] * rstd * ga + be; *(f32x4*)(xr + col) = v[j]; s += (v[j].x + v[j].y) + (v[j].z + v[j].w); }
;         mean = wave_sum(s, lane) * (1.f / DM); s2 = 0.f;
; #pragma unroll
;         for (int j = 0; j < 4; ++j) { v[j] = v[j] - mean; s2 += (v[j].x * v[j].x + v[j].y * v[j].y) + (v[j].z * v[j].z + v[j].w * v[j].w); }
;         rstd = __builtin_amdgcn_rsqf(wave_sum(s2, lane) * (1.f / DM) + 1e-6f);
; #pragma unroll
;         for (int j = 0; j < 4; ++j) { const int col = 4 * lane + 256 * j; const f32x4 a = *(const f32x4*)(sc + col), bb = *(const f32x4*)(sh + col);
	v_pk_fma_f32 v[56:57], v[16:17], v[56:57], v[20:21]
	v_pk_fma_f32 v[58:59], v[18:19], v[58:59], v[22:23]
	v_pk_fma_f32 v[62:63], v[26:27], v[62:63], v[30:31]
	v_pk_fma_f32 v[60:61], v[24:25], v[60:61], v[28:29]
	v_add_f32_e32 v83, v56, v57
	v_add_f32_e32 v85, v58, v59
	v_mov_b32_e32 v82, v60
	v_mov_b32_e32 v84, v61
	v_mov_b32_e32 v102, v62
	v_mov_b32_e32 v98, v63
	v_pk_add_f32 v[80:81], v[82:83], v[84:85]
	v_pk_add_f32 v[82:83], v[102:103], v[98:99]
	global_store_dwordx4 v[100:101], v[52:55], off offset:1024
	v_pk_add_f32 v[80:81], v[80:81], v[82:83]
	global_store_dwordx4 v[100:101], v[56:59], off offset:2048
	v_add_f32_e32 v80, v80, v81
	global_store_dwordx4 v[100:101], v[60:63], off offset:3072
	s_nop 1
	v_add_f32_dpp v80, v80, v80 quad_perm:[1,0,3,2] row_mask:0xf bank_mask:0xf
	s_nop 1
	v_add_f32_dpp v80, v80, v80 quad_perm:[2,3,0,1] row_mask:0xf bank_mask:0xf
	s_nop 1
	v_add_f32_dpp v80, v80, v80 row_half_mirror row_mask:0xf bank_mask:0xf
	s_nop 1
	v_add_f32_dpp v80, v80, v80 row_mirror row_mask:0xf bank_mask:0xf
	v_mov_b32_e32 v81, v80
	s_nop 1
	v_permlane16_swap_b32_e32 v80, v81
	v_add_f32_e32 v80, v80, v81
	v_mov_b32_e32 v81, v80
	s_nop 1
	v_permlane32_swap_b32_e32 v80, v81
	v_add_f32_e32 v98, v80, v81
	v_fmamk_f32 v49, v98, 0xba800000, v49
	v_fmac_f32_e32 v48, 0xba800000, v98
	v_fmamk_f32 v51, v98, 0xba800000, v51
	v_fmac_f32_e32 v50, 0xba800000, v98
	v_pk_mul_f32 v[80:81], v[50:51], v[50:51]
	v_pk_mul_f32 v[82:83], v[48:49], v[48:49]
	v_fmamk_f32 v53, v98, 0xba800000, v53
	v_pk_mov_b32 v[84:85], v[82:83], v[80:81] op_sel:[1,0]
	v_mov_b32_e32 v83, v81
	v_pk_add_f32 v[80:81], v[84:85], v[82:83]
	v_fmac_f32_e32 v52, 0xba800000, v98
	v_fmamk_f32 v55, v98, 0xba800000, v55
	v_fmac_f32_e32 v54, 0xba800000, v98
	v_pk_add_f32 v[80:81], v[80:81], v[80:81] op_sel_hi:[0,1]
	v_pk_mul_f32 v[82:83], v[54:55], v[54:55]
	v_pk_mul_f32 v[84:85], v[52:53], v[52:53]
	v_fmac_f32_e32 v56, 0xba800000, v98
	v_pk_mov_b32 v[86:87], v[84:85], v[82:83] op_sel:[1,0]
	v_mov_b32_e32 v85, v83
	v_fmamk_f32 v57, v98, 0xba800000, v57
	v_fmac_f32_e32 v58, 0xba800000, v98
	v_mul_f32_e32 v80, v56, v56
	v_pk_add_f32 v[82:83], v[86:87], v[84:85]
	v_fmamk_f32 v59, v98, 0xba800000, v59
	v_pk_fma_f32 v[84:85], v[56:57], v[56:57], v[80:81] op_sel_hi:[1,1,0]
	v_mul_f32_e32 v80, v58, v58
	v_pk_add_f32 v[82:83], v[82:83], v[82:83] op_sel_hi:[0,1]
	v_pk_fma_f32 v[86:87], v[58:59], v[58:59], v[80:81] op_sel_hi:[1,1,0]
	v_fmamk_f32 v63, v98, 0xba800000, v63
	v_fmac_f32_e32 v62, 0xba800000, v98
	v_fmamk_f32 v61, v98, 0xba800000, v61
	v_fmac_f32_e32 v60, 0xba800000, v98
	v_mul_f32_e32 v84, v60, v60
	v_mul_f32_e32 v86, v61, v61
	v_mul_f32_e32 v80, v62, v62
	v_mul_f32_e32 v82, v63, v63
	v_pk_add_f32 v[84:85], v[84:85], v[86:87]
	v_pk_add_f32 v[80:81], v[80:81], v[82:83]
	s_nop 0
	v_pk_add_f32 v[80:81], v[84:85], v[80:81]
	v_add_f32_e32 v80, v80, v81
	s_nop 1
	v_add_f32_dpp v80, v80, v80 quad_perm:[1,0,3,2] row_mask:0xf bank_mask:0xf
	s_nop 1
	v_add_f32_dpp v80, v80, v80 quad_perm:[2,3,0,1] row_mask:0xf bank_mask:0xf
	s_nop 1
	v_add_f32_dpp v80, v80, v80 row_half_mirror row_mask:0xf bank_mask:0xf
	s_nop 1
	v_add_f32_dpp v80, v80, v80 row_mirror row_mask:0xf bank_mask:0xf
	v_mov_b32_e32 v81, v80
	s_nop 1
	v_permlane16_swap_b32_e32 v80, v81
	v_add_f32_e32 v80, v80, v81
	v_mov_b32_e32 v81, v80
	s_nop 1
	v_permlane32_swap_b32_e32 v80, v81
	v_add_f32_e32 v80, v80, v81
	v_fmamk_f32 v80, v80, 0x3a800000, v238
	v_rsq_f32_e32 v80, v80
	s_cmp_lg_u32 s11, 0
	s_cbranch_scc0 .Lln1_w4
	s_waitcnt vmcnt(12)
	s_branch .Lln1_wd
.Lln1_w4:
	s_waitcnt vmcnt(4)
; __device__ __forceinline__ unsigned cvt_pk_bf16(float lo, float hi) { unsigned r; asm volatile("s_nop 0\n\tv_cvt_pk_bf16_f32 %0, %1, %2\n\ts_nop 1" : "=v"(r) : "v"(lo), "v"(hi)); return r; }
; __device__ __forceinline__ float bflo(unsigned w) { return __uint_as_float(w << 16); }
; __device__ __forceinline__ void phase_ln1(const Params& p, int g, int gw, int NGW, int lane) {
;     ...
;     for (int row = gw; row < TG; row += NGW) {
;         const int b = g * BG + row / SEQ; const float* sh = mod + (size_t)b * MODW + 3 * DM; const float* sc = sh + DM;
;         float* xr = x1 + (size_t)row * DM;
;         f32x4 v[4]; float s = 0.f;
; #pragma unroll
;         for (int j = 0; j < 4; ++j) { const u32x2 bw = nb[j];
;             v[j] = nx[j] * ALPHA + (f32x4){bflo(bw.x), bfhi(bw.x), bflo(bw.y), bfhi(bw.y)}; s += (v[j].x + v[j].y) + (v[j].z + v[j].w); }
;         if (row + NGW < TG) { const size_t nr = (size_t)(row + NGW) * DM;
; #pragma unroll
;             for (int j = 0; j < 4; ++j) { nx[j] = *(const f32x4*)(xbase + nr + 4 * lane + 256 * j); nb[j] = *(const u32x2*)(brbase + nr + 4 * lane + 256 * j); } }
;         float mean = wave_sum(s, lane) * (1.f / DM); float s2 = 0.f;
; #pragma unroll
;         for (int j = 0; j < 4; ++j) { v[j] = v[j] - mean; s2 += (v[j].x * v[j].x + v[j].y * v[j].y) + (v[j].z * v[j].z + v[j].w * v[j].w); }
;         float rstd = __builtin_amdgcn_rsqf(wave_sum(s2, lane) * (1.f / DM) + 1e-6f);
;         s = 0.f;
; #pragma unroll
;         for (int j = 0; j < 4; ++j) { const int col = 4 * lane + 256 * j; const f32x4 ga = gaH[j], be = beH[j];
;             v[j] = v[j] * rstd * ga + be; *(f32x4*)(xr + col) = v[j]; s += (v[j].x + v[j].y) + (v[j].z + v[j].w); }
;         mean = wave_sum(s, lane) * (1.f / DM); s2 = 0.f;
; #pragma unroll
;         for (int j = 0; j < 4; ++j) { v[j] = v[j] - mean; s2 += (v[j].x * v[j].x + v[j].y * v[j].y) + (v[j].z * v[j].z + v[j].w * v[j].w); }
;         rstd = __builtin_amdgcn_rsqf(wave_sum(s2, lane) * (1.f / DM) + 1e-6f);
; #pragma unroll
;         for (int j = 0; j < 4; ++j) { const int col = 4 * lane + 256 * j; const f32x4 a = *(const f32x4*)(sc + col), bb = *(const f32x4*)(sh + col);
;             const f32x4 o = v[j] * rstd * (a + 1.f) + bb; u32x2 w; w.x = cvt_pk_bf16(o.x, o.y); w.y = cvt_pk_bf16(o.z, o.w);
;             *(u32x2*)(h1 + (size_t)row * DM + col) = w; }
.Lln1_wd:
	v_pk_add_f32 v[84:85], v[154:155], 1.0 op_sel_hi:[1,0]
	v_pk_mul_f32 v[48:49], v[48:49], v[80:81] op_sel_hi:[1,0]
	v_pk_mul_f32 v[50:51], v[50:51], v[80:81] op_sel_hi:[1,0]
	v_pk_add_f32 v[82:83], v[152:153], 1.0 op_sel_hi:[1,0]
	v_pk_fma_f32 v[50:51], v[84:85], v[50:51], v[158:159]
	v_pk_fma_f32 v[48:49], v[82:83], v[48:49], v[156:157]
	v_pk_mul_f32 v[52:53], v[52:53], v[80:81] op_sel_hi:[1,0]
	v_cvt_pk_bf16_f32 v48, v48, v49
	v_cvt_pk_bf16_f32 v49, v50, v51
	v_lshl_add_u64 v[50:51], s[94:95], 0, v[70:71]
	v_add_co_u32_e32 v86, vcc, s1, v50
	v_pk_mul_f32 v[54:55], v[54:55], v[80:81] op_sel_hi:[1,0]
	s_nop 0
	v_addc_co_u32_e32 v87, vcc, 0, v51, vcc
	global_store_dwordx2 v[86:87], v[48:49], off
	s_nop 0
	v_pk_mul_f32 v[56:57], v[56:57], v[80:81] op_sel_hi:[1,0]
	v_pk_mul_f32 v[58:59], v[58:59], v[80:81] op_sel_hi:[1,0]
	s_and_b64 vcc, exec, s[2:3]
	v_pk_add_f32 v[48:49], v[104:105], 1.0 op_sel_hi:[1,0]
	v_pk_add_f32 v[50:51], v[106:107], 1.0 op_sel_hi:[1,0]
	v_pk_fma_f32 v[48:49], v[48:49], v[52:53], v[108:109]
	v_pk_fma_f32 v[50:51], v[50:51], v[54:55], v[110:111]
	v_cvt_pk_bf16_f32 v48, v48, v49
	v_cvt_pk_bf16_f32 v49, v50, v51
	global_store_dwordx2 v[86:87], v[48:49], off offset:512
	s_nop 0
	v_pk_add_f32 v[48:49], v[112:113], 1.0 op_sel_hi:[1,0]
	v_pk_add_f32 v[50:51], v[114:115], 1.0 op_sel_hi:[1,0]
	v_pk_fma_f32 v[48:49], v[48:49], v[56:57], v[116:117]
	v_pk_fma_f32 v[50:51], v[50:51], v[58:59], v[118:119]
	v_cvt_pk_bf16_f32 v48, v48, v49
	v_pk_mul_f32 v[56:57], v[60:61], v[80:81] op_sel_hi:[1,0]
	v_cvt_pk_bf16_f32 v49, v50, v51
	global_store_dwordx2 v[86:87], v[48:49], off offset:1024
	s_nop 0
	v_readlane_b32 s4, v255, 2
	v_readlane_b32 s5, v255, 3
	v_pk_mul_f32 v[58:59], v[62:63], v[80:81] op_sel_hi:[1,0]
	v_lshl_add_u64 v[70:71], v[70:71], 0, s[4:5]
	v_readlane_b32 s4, v255, 0
	v_readlane_b32 s5, v255, 1
	v_lshl_add_u64 v[68:69], v[68:69], 0, s[4:5]
	s_mov_b32 s4, s0
	v_pk_add_f32 v[48:49], v[120:121], 1.0 op_sel_hi:[1,0]
	v_pk_add_f32 v[50:51], v[122:123], 1.0 op_sel_hi:[1,0]
	v_pk_fma_f32 v[48:49], v[48:49], v[56:57], v[124:125]
	v_pk_fma_f32 v[50:51], v[50:51], v[58:59], v[126:127]
	v_cvt_pk_bf16_f32 v48, v48, v49
	v_cvt_pk_bf16_f32 v49, v50, v51
	global_store_dwordx2 v[86:87], v[48:49], off offset:1536
	s_cmp_eq_u32 s10, 0
	s_cbranch_scc0 .Lln1_fromC
	v_mov_b64_e32 v[82:83], v[74:75]
	v_mov_b64_e32 v[84:85], v[76:77]
	v_mov_b64_e32 v[80:81], v[72:73]
	v_mov_b64_e32 v[86:87], v[78:79]
	v_mov_b32_e32 v60, v32
	v_mov_b32_e32 v61, v33
	v_mov_b32_e32 v62, v34
	v_mov_b32_e32 v63, v35
	v_mov_b32_e32 v56, v36
	v_mov_b32_e32 v57, v37
	v_mov_b32_e32 v58, v38
	v_mov_b32_e32 v59, v39
	v_mov_b32_e32 v52, v40
	v_mov_b32_e32 v53, v41
	v_mov_b32_e32 v54, v42
	v_mov_b32_e32 v55, v43
	v_mov_b32_e32 v48, v44
	v_mov_b32_e32 v49, v45
	v_mov_b32_e32 v50, v46
	v_mov_b32_e32 v51, v47
	s_branch .Lln1_cpd
.Lln1_fromC:
	v_mov_b64_e32 v[82:83], v[146:147]
	v_mov_b64_e32 v[84:85], v[148:149]
	v_mov_b64_e32 v[80:81], v[144:145]
	v_mov_b64_e32 v[86:87], v[150:151]
	v_mov_b32_e32 v60, v128
	v_mov_b32_e32 v61, v129
	v_mov_b32_e32 v62, v130
	v_mov_b32_e32 v63, v131
	v_mov_b32_e32 v56, v132
	v_mov_b32_e32 v57, v133
	v_mov_b32_e32 v58, v134
	v_mov_b32_e32 v59, v135
	v_mov_b32_e32 v52, v136
	v_mov_b32_e32 v53, v137
	v_mov_b32_e32 v54, v138
	v_mov_b32_e32 v55, v139
	v_mov_b32_e32 v48, v140
	v_mov_b32_e32 v49, v141
	v_mov_b32_e32 v50, v142
	v_mov_b32_e32 v51, v143
.Lln1_cpd:
	s_xor_b32 s10, s10, 1
	s_cbranch_vccnz .LBB0_308
.LBB0_306:
	v_readlane_b32 s0, v255, 12
	s_nop 1
	s_add_i32 s8, s0, s0
	s_add_i32 s8, s4, s8
	s_add_i32 s0, s4, s0
	s_cmpk_gt_i32 s0, 0x7fff
	s_cselect_b64 s[2:3], -1, 0
	s_ashr_i32 s1, s4, 31
	s_lshr_b32 s1, s1, 21
	s_add_i32 s1, s4, s1
	s_ashr_i32 s1, s1, 11
	s_add_i32 s1, s1, s76
	s_mul_hi_i32 s4, s1, 0x6000
	s_mulk_i32 s1, 0x6000
	s_add_u32 s1, s94, s1
	s_addc_u32 s7, s95, s4
	s_add_u32 s4, s1, 0x3000
	s_addc_u32 s5, s7, 0
	s_add_u32 s6, s1, 0x4000
	s_addc_u32 s7, s7, 0
	global_load_dwordx4 v[152:155], v94, s[6:7]
	global_load_dwordx4 v[156:159], v94, s[4:5]
	global_load_dwordx4 v[104:107], v95, s[6:7]
	global_load_dwordx4 v[108:111], v95, s[4:5]
	global_load_dwordx4 v[112:115], v96, s[6:7]
	global_load_dwordx4 v[116:119], v96, s[4:5]
	global_load_dwordx4 v[120:123], v97, s[6:7]
	global_load_dwordx4 v[124:127], v97, s[4:5]
	s_mov_b32 s11, 0
	s_cmpk_gt_i32 s8, 0x7fff
	s_cbranch_scc1 .LBB0_305
	s_mov_b32 s11, 1
	s_ashr_i32 s9, s8, 31
	s_cmp_eq_u32 s10, 0
	s_cbranch_scc0 .Lln1_toB
	s_lshl_b64 s[6:7], s[8:9], 12
	v_lshl_add_u64 v[140:141], v[66:67], 0, s[6:7]
	s_lshl_b64 s[6:7], s[8:9], 11
	v_lshl_add_u64 v[144:145], v[64:65], 0, s[6:7]
	global_load_dwordx4 v[128:131], v[140:141], off
	global_load_dwordx4 v[132:135], v[140:141], off offset:1024
	global_load_dwordx4 v[136:139], v[140:141], off offset:2048
	s_nop 0
	global_load_dwordx4 v[140:143], v[140:141], off offset:3072
	s_nop 0
	global_load_dwordx2 v[150:151], v[144:145], off
	global_load_dwordx2 v[148:149], v[144:145], off offset:512
	global_load_dwordx2 v[146:147], v[144:145], off offset:1024
	s_nop 0
	global_load_dwordx2 v[144:145], v[144:145], off offset:1536
	s_branch .LBB0_305
.Lln1_toB:
	s_lshl_b64 s[6:7], s[8:9], 12
	v_lshl_add_u64 v[44:45], v[66:67], 0, s[6:7]
	s_lshl_b64 s[6:7], s[8:9], 11
	v_lshl_add_u64 v[72:73], v[64:65], 0, s[6:7]
	global_load_dwordx4 v[32:35], v[44:45], off
	global_load_dwordx4 v[36:39], v[44:45], off offset:1024
	global_load_dwordx4 v[40:43], v[44:45], off offset:2048
	s_nop 0
	global_load_dwordx4 v[44:47], v[44:45], off offset:3072
	s_nop 0
	global_load_dwordx2 v[78:79], v[72:73], off
	global_load_dwordx2 v[76:77], v[72:73], off offset:512
	global_load_dwordx2 v[74:75], v[72:73], off offset:1024
	s_nop 0
	global_load_dwordx2 v[72:73], v[72:73], off offset:1536
	s_branch .LBB0_305
